# baseline (speedup 1.0000x reference)
; #define MFMA32(a, b, c) __builtin_amdgcn_mfma_f32_32x32x16_bf16((a), (b), (c), 0, 0, 0)
; template <int MODE>
; DI void attn_item(const u16* __restrict__ Qp, const u16* __restrict__ Kp, const u16* __restrict__ VTp, int q0,
;                   int kt_lo, int kt_hi, u16* __restrict__ Op, int os, float* __restrict__ lsep, int ls, char* lds, int tid) {
;     ...
;       float psum = 0.f;
; #pragma unroll
;       for (int mt = 0; mt < NMT; mt++)
; #pragma unroll
;         for (int r = 0; r < 16; r++) {
;           const float p = __builtin_amdgcn_exp2f(st[mt][r] - m_new);
;           psum += p;
;           st[mt][r] = p;
;         }
;       l_run = l_run * alpha + psum;
;     ...
; #pragma unroll
;     for (int s4 = 0; s4 < NS4; s4++) {
;       const int mt = s4 >> 1, r0 = (s4 & 1) * 8;
;       uint4 pw;
;       pw.x = pack2(st[mt][r0 + 0], st[mt][r0 + 1]);
;       pw.y = pack2(st[mt][r0 + 2], st[mt][r0 + 3]);
;       pw.z = pack2(st[mt][r0 + 4], st[mt][r0 + 5]);
;       pw.w = pack2(st[mt][r0 + 6], st[mt][r0 + 7]);
;       const bf16x8 pb = __builtin_bit_cast(bf16x8, pw);
; #pragma unroll
;       for (int dt = 0; dt < 4; dt++) {
;         const char* vr = Vs + (dt * 32 + c) * VROW + (16 * s4 + 4 * h) * 2;
;         const bf16x4 lo = *(const bf16x4*)(vr);
;         const bf16x4 hi = *(const bf16x4*)(vr + 16);
;         const bf16x8 vf = __builtin_shufflevector(lo, hi, 0, 1, 2, 3, 4, 5, 6, 7);
;         ot[dt] = MFMA32(vf, pb, ot[dt]);
;       }
;     }
.Lp4_noresc:
.Lp4_pv:
	v_cvt_pk_bf16_f32 v67, v225, v226
	s_add_i32 s42, s42, 1
	s_andn2_b64 vcc, exec, s[12:13]
	s_waitcnt lgkmcnt(4)
	s_nop 0
	s_setprio 1
	v_mfma_f32_32x32x16_bf16 v[48:63], v[236:239], v[64:67], v[48:63]
	ds_read_b64 v[236:237], v252 offset:17952
	ds_read_b64 v[238:239], v252 offset:17968
	v_add_f32_e32 v235, 0, v219
	v_add_f32_e32 v235, v235, v220
	v_mfma_f32_32x32x16_bf16 v[32:47], v[240:243], v[64:67], v[32:47]
	ds_read_b64 v[240:241], v252 offset:20512
	ds_read_b64 v[242:243], v252 offset:20528
	v_add_f32_e32 v235, v235, v221
	v_add_f32_e32 v235, v235, v222
	v_mfma_f32_32x32x16_bf16 v[16:31], v[244:247], v[64:67], v[16:31]
	v_add_f32_e32 v235, v235, v223
	v_add_f32_e32 v235, v235, v224
	v_mfma_f32_32x32x16_bf16 v[0:15], v[248:251], v[64:67], v[0:15]
	v_cvt_pk_bf16_f32 v64, v227, v228
	v_cvt_pk_bf16_f32 v65, v229, v230
	v_cvt_pk_bf16_f32 v66, v231, v232
	v_cvt_pk_bf16_f32 v67, v233, v234
	v_add_f32_e32 v235, v235, v225
	v_add_f32_e32 v235, v235, v226
	s_waitcnt lgkmcnt(4)
	s_nop 0
	v_mfma_f32_32x32x16_bf16 v[32:47], v[74:77], v[64:67], v[32:47]
	v_add_f32_e32 v235, v235, v227
	v_add_f32_e32 v235, v235, v228
	s_waitcnt lgkmcnt(2)
	v_mfma_f32_32x32x16_bf16 v[16:31], v[236:239], v[64:67], v[16:31]
	v_add_f32_e32 v235, v235, v229
	v_add_f32_e32 v235, v235, v230
	v_mfma_f32_32x32x16_bf16 v[48:63], v[70:73], v[64:67], v[48:63]
	v_add_f32_e32 v235, v235, v231
	v_add_f32_e32 v235, v235, v232
	v_add_f32_e32 v235, v235, v233
	v_add_f32_e32 v235, v235, v234
	s_waitcnt lgkmcnt(0)
	v_mfma_f32_32x32x16_bf16 v[0:15], v[240:243], v[64:67], v[0:15]
	s_setprio 0
	s_cbranch_vccnz .LBB0_473
	s_bitcmp1_b32 s42, 0
	s_cselect_b32 s11, 0x5a00, 0
	v_add3_u32 v64, s11, v209, v174
	s_waitcnt vmcnt(4)
	ds_write_b128 v64, v[128:131]
	s_waitcnt vmcnt(3)
	ds_write_b128 v64, v[132:135] offset:128
	s_waitcnt vmcnt(2)
	ds_write_b128 v64, v[136:139] offset:256
	v_add3_u32 v64, s11, v177, v175
	s_waitcnt vmcnt(1)
	ds_write_b128 v64, v[140:143] offset:12800
	s_waitcnt vmcnt(0)
	ds_write_b128 v64, v[144:147] offset:17920
.LBB0_473:
	v_mov_b32_e32 v64, v235
	s_add_i32 s10, s10, 32
	v_fmac_f32_e32 v64, v150, v68
	s_cmp_lg_u32 s46, s42
	s_waitcnt lgkmcnt(0)
	s_barrier
	s_cbranch_scc0 .LBB0_426
	v_mov_b32_e32 v150, v64
	v_mov_b32_e32 v218, v217
	s_cmp_lt_u32 s42, s43
	s_cselect_b64 s[12:13], -1, 0
	s_cmp_ge_u32 s42, s43
	s_cbranch_scc0 .LBB0_466
	s_branch .LBB0_467
